# one-sided attention masks (2 VALU per element) + MODE1 half-tile paths for half-dead tiles
# speedup vs baseline: 1.0182x; 1.0072x over previous
.LBB0_393:
	v_cmp_neq_f32_e32 vcc, 0, v212
	s_cbranch_vccnz .Lm1_full
	s_add_i32 s10, s80, 63
	s_cmp_ge_i32 s92, s10
	s_cbranch_scc0 .Lm1_chk_p0
	s_cmpk_lt_i32 s93, 0x81
	s_cbranch_scc1 .Lm1h_p0
	s_branch .Lm1_full
.Lm1_chk_p0:
	s_add_i32 s10, s80, 0xffffffa0
	s_cmp_lt_i32 s92, s10
	s_cbranch_scc1 .Lm1h_p1

.LBB0_395:
	s_cmp_le_i32 s92, s80
	s_cselect_b64 s[10:11], -1, 0
	s_cmpk_lt_i32 s93, 0x81
	s_cselect_b64 s[12:13], -1, 0
	s_and_b64 s[14:15], s[10:11], s[12:13]
	s_and_b64 vcc, exec, s[14:15]
	s_cbranch_vccnz .LBB0_399
	s_and_b64 vcc, exec, s[10:11]
	s_cbranch_vccnz .Lmk_lo_1
	s_and_b64 vcc, exec, s[12:13]
	s_cbranch_vccnz .Lmk_up_1
	v_add_u32_e32 v152, s92, v156
	v_subrev_u32_e32 v218, 31, v152
	v_cmp_le_i32_e64 s[12:13], v218, v213
	v_cmp_ge_i32_e64 s[14:15], v218, v214
	v_subrev_u32_e32 v217, 63, v152
	s_and_b64 s[12:13], s[12:13], s[14:15]
	v_cmp_le_i32_e32 vcc, v217, v213
	v_cmp_ge_i32_e64 s[10:11], v217, v214
	v_cndmask_b32_e64 v48, v229, v48, s[12:13]
	v_subrev_u32_e32 v218, 62, v152
	v_cmp_lt_i32_e64 s[12:13], v217, v213
	v_subrev_u32_e32 v217, 30, v152
	v_cmp_le_i32_e64 s[16:17], v217, v213
	v_cmp_ge_i32_e64 s[14:15], v218, v214
	v_cmp_ge_i32_e64 s[18:19], v217, v214
	v_subrev_u32_e32 v218, 29, v152
	s_and_b64 s[16:17], s[16:17], s[18:19]
	v_subrev_u32_e32 v217, 61, v152
	v_cmp_le_i32_e64 s[20:21], v218, v213
	v_cmp_ge_i32_e64 s[22:23], v218, v214
	v_subrev_u32_e32 v218, 28, v152
	v_cndmask_b32_e64 v49, v229, v49, s[16:17]
	v_cmp_le_i32_e64 s[16:17], v217, v213
	v_cmp_ge_i32_e64 s[18:19], v217, v214
	s_and_b64 s[20:21], s[20:21], s[22:23]
	v_subrev_u32_e32 v217, 60, v152
	v_cmp_le_i32_e64 s[24:25], v218, v213
	v_cmp_ge_i32_e64 s[26:27], v218, v214
	v_subrev_u32_e32 v218, 23, v152
	v_cndmask_b32_e64 v50, v229, v50, s[20:21]
	v_cmp_le_i32_e64 s[20:21], v217, v213
	v_cmp_ge_i32_e64 s[22:23], v217, v214
	s_and_b64 s[24:25], s[24:25], s[26:27]
	v_subrev_u32_e32 v217, 55, v152
	v_cmp_le_i32_e64 s[28:29], v218, v213
	v_cmp_ge_i32_e64 s[30:31], v218, v214
	v_subrev_u32_e32 v218, 22, v152
	v_cndmask_b32_e64 v51, v229, v51, s[24:25]
	v_cmp_le_i32_e64 s[24:25], v217, v213
	v_cmp_ge_i32_e64 s[26:27], v217, v214
	s_and_b64 s[28:29], s[28:29], s[30:31]
	v_subrev_u32_e32 v217, 54, v152
	v_cmp_le_i32_e64 s[34:35], v218, v213
	v_cmp_ge_i32_e64 s[36:37], v218, v214
	v_subrev_u32_e32 v218, 21, v152
	v_cndmask_b32_e64 v52, v229, v52, s[28:29]
	v_cmp_le_i32_e64 s[28:29], v217, v213
	v_cmp_ge_i32_e64 s[30:31], v217, v214
	s_and_b64 s[34:35], s[34:35], s[36:37]
	v_subrev_u32_e32 v217, 53, v152
	v_cmp_le_i32_e64 s[38:39], v218, v213
	v_cmp_ge_i32_e64 s[40:41], v218, v214
	v_subrev_u32_e32 v218, 20, v152
	v_cndmask_b32_e64 v53, v229, v53, s[34:35]
	v_cmp_le_i32_e64 s[34:35], v217, v213
	v_cmp_ge_i32_e64 s[36:37], v217, v214
	s_and_b64 s[38:39], s[38:39], s[40:41]
	v_subrev_u32_e32 v217, 52, v152
	v_cmp_le_i32_e64 s[42:43], v218, v213
	v_cmp_ge_i32_e64 s[44:45], v218, v214
	v_add_u32_e32 v218, -15, v152
	v_cndmask_b32_e64 v54, v229, v54, s[38:39]
	v_cmp_le_i32_e64 s[38:39], v217, v213
	v_cmp_ge_i32_e64 s[40:41], v217, v214
	s_and_b64 s[42:43], s[42:43], s[44:45]
	v_subrev_u32_e32 v217, 47, v152
	v_cmp_le_i32_e64 s[46:47], v218, v213
	v_cmp_ge_i32_e64 s[48:49], v218, v214
	v_add_u32_e32 v218, -14, v152
	v_cndmask_b32_e64 v55, v229, v55, s[42:43]
	v_cmp_le_i32_e64 s[42:43], v217, v213
	v_cmp_ge_i32_e64 s[44:45], v217, v214
	s_and_b64 s[46:47], s[46:47], s[48:49]
	v_subrev_u32_e32 v217, 46, v152
	v_cmp_le_i32_e64 s[50:51], v218, v213
	v_cmp_ge_i32_e64 s[52:53], v218, v214
	v_add_u32_e32 v218, -13, v152
	v_cndmask_b32_e64 v56, v229, v56, s[46:47]
	v_cmp_le_i32_e64 s[46:47], v217, v213
	v_cmp_ge_i32_e64 s[48:49], v217, v214
	s_and_b64 s[50:51], s[50:51], s[52:53]
	v_subrev_u32_e32 v217, 45, v152
	v_cmp_le_i32_e64 s[54:55], v218, v213
	v_cmp_ge_i32_e64 s[56:57], v218, v214
	v_add_u32_e32 v218, -12, v152
	v_cndmask_b32_e64 v57, v229, v57, s[50:51]
	v_cmp_le_i32_e64 s[50:51], v217, v213
	v_cmp_ge_i32_e64 s[52:53], v217, v214
	s_and_b64 s[54:55], s[54:55], s[56:57]
	v_subrev_u32_e32 v217, 44, v152
	v_cmp_le_i32_e64 s[58:59], v218, v213
	v_cmp_ge_i32_e64 s[60:61], v218, v214
	v_add_u32_e32 v218, -7, v152
	v_cndmask_b32_e64 v58, v229, v58, s[54:55]
	v_cmp_le_i32_e64 s[54:55], v217, v213
	v_cmp_ge_i32_e64 s[56:57], v217, v214
	s_and_b64 s[58:59], s[58:59], s[60:61]
	v_subrev_u32_e32 v217, 39, v152
	v_cmp_le_i32_e64 s[62:63], v218, v213
	v_cmp_ge_i32_e64 s[64:65], v218, v214
	v_add_u32_e32 v218, -6, v152
	v_cndmask_b32_e64 v59, v229, v59, s[58:59]
	v_cmp_le_i32_e64 s[58:59], v217, v213
	v_cmp_ge_i32_e64 s[60:61], v217, v214
	s_and_b64 s[62:63], s[62:63], s[64:65]
	v_subrev_u32_e32 v217, 38, v152
	v_cmp_le_i32_e64 s[66:67], v218, v213
	v_cmp_ge_i32_e64 s[68:69], v218, v214
	v_cndmask_b32_e64 v60, v229, v60, s[62:63]
	v_cmp_le_i32_e64 s[62:63], v217, v213
	v_cmp_ge_i32_e64 s[64:65], v217, v214
	s_and_b64 s[66:67], s[66:67], s[68:69]
	v_subrev_u32_e32 v217, 37, v152
	v_add_u32_e32 v218, -5, v152
	v_cndmask_b32_e64 v61, v229, v61, s[66:67]
	v_cmp_le_i32_e64 s[66:67], v217, v213
	v_cmp_le_i32_e64 s[70:71], v218, v213
	v_cmp_ge_i32_e64 s[68:69], v217, v214
	v_cmp_ge_i32_e64 s[72:73], v218, v214
	v_subrev_u32_e32 v217, 36, v152
	v_add_u32_e32 v152, -4, v152
	s_and_b64 s[70:71], s[70:71], s[72:73]
	v_cmp_gt_i32_e64 s[76:77], v152, v213
	v_cmp_lt_i32_e64 s[78:79], v152, v214
	v_cndmask_b32_e64 v62, v229, v62, s[70:71]
	v_cmp_le_i32_e64 s[70:71], v217, v213
	v_cmp_ge_i32_e64 s[72:73], v217, v214
	s_or_b64 s[78:79], s[76:77], s[78:79]
	s_and_saveexec_b64 s[76:77], s[78:79]
	v_mov_b32_e32 v63, s0
	s_or_b64 exec, exec, s[76:77]
	s_and_b64 vcc, vcc, s[10:11]
	v_cndmask_b32_e32 v32, v229, v32, vcc
	s_and_b64 vcc, s[12:13], s[14:15]
	v_cndmask_b32_e32 v33, v229, v33, vcc
	s_and_b64 vcc, s[16:17], s[18:19]
	v_cndmask_b32_e32 v34, v229, v34, vcc
	s_and_b64 vcc, s[20:21], s[22:23]
	v_cndmask_b32_e32 v35, v229, v35, vcc
	s_and_b64 vcc, s[24:25], s[26:27]
	v_cndmask_b32_e32 v36, v229, v36, vcc
	s_and_b64 vcc, s[28:29], s[30:31]
	v_cndmask_b32_e32 v37, v229, v37, vcc
	s_and_b64 vcc, s[34:35], s[36:37]
	v_cndmask_b32_e32 v38, v229, v38, vcc
	s_and_b64 vcc, s[38:39], s[40:41]
	v_cndmask_b32_e32 v39, v229, v39, vcc
	s_and_b64 vcc, s[42:43], s[44:45]
	v_cndmask_b32_e32 v40, v229, v40, vcc
	s_and_b64 vcc, s[46:47], s[48:49]
	v_cndmask_b32_e32 v41, v229, v41, vcc
	s_and_b64 vcc, s[50:51], s[52:53]
	v_cndmask_b32_e32 v42, v229, v42, vcc
	s_and_b64 vcc, s[54:55], s[56:57]
	v_cndmask_b32_e32 v43, v229, v43, vcc
	s_and_b64 vcc, s[58:59], s[60:61]
	v_cndmask_b32_e32 v44, v229, v44, vcc
	s_and_b64 vcc, s[62:63], s[64:65]
	v_cndmask_b32_e32 v45, v229, v45, vcc
	s_and_b64 vcc, s[66:67], s[68:69]
	v_cndmask_b32_e32 v46, v229, v46, vcc
	s_and_b64 vcc, s[70:71], s[72:73]
	v_cndmask_b32_e32 v47, v229, v47, vcc

.Lm1_old400:
	v_max_f32_e32 v152, v152, v152
	v_max_f32_e32 v152, 0, v152
	v_exp_f32_e64 v217, -v152
	s_and_saveexec_b64 s[10:11], s[4:5]
	s_cbranch_execz .LBB0_391
	ds_write_b32 v157, v217
	s_branch .LBB0_391

.Lm1h_p0:
	ds_read_b128 v[48:51], v216
	ds_read_b128 v[52:55], v216 offset:2080
	ds_read_b128 v[56:59], v216 offset:4160
	ds_read_b128 v[60:63], v216 offset:6240
	s_waitcnt lgkmcnt(3)
	v_mfma_f32_32x32x16_bf16 v[32:47], v[48:51], v[140:143], 0
	s_waitcnt lgkmcnt(2)
	v_mfma_f32_32x32x16_bf16 v[32:47], v[52:55], v[136:139], v[32:47]
	s_waitcnt lgkmcnt(1)
	v_mfma_f32_32x32x16_bf16 v[32:47], v[56:59], v[132:135], v[32:47]
	s_waitcnt lgkmcnt(0)
	v_mfma_f32_32x32x16_bf16 v[32:47], v[60:63], v[128:131], v[32:47]
	v_add_u32_e32 v217, s92, v156
	v_subrev_u32_e32 v217, 63, v217
	v_sub_u32_e32 v217, v213, v217
	s_nop 8
	v_cmp_le_i32_e64 s[10:11], 0, v217
	v_cmp_le_i32_e64 s[12:13], 1, v217
	v_cmp_le_i32_e64 s[14:15], 2, v217
	v_cndmask_b32_e64 v32, v229, v32, s[10:11]
	v_cmp_le_i32_e64 s[16:17], 3, v217
	v_cndmask_b32_e64 v33, v229, v33, s[12:13]
	v_cmp_le_i32_e64 s[10:11], 8, v217
	v_cndmask_b32_e64 v34, v229, v34, s[14:15]
	v_cmp_le_i32_e64 s[12:13], 9, v217
	v_cndmask_b32_e64 v35, v229, v35, s[16:17]
	v_cmp_le_i32_e64 s[14:15], 10, v217
	v_cndmask_b32_e64 v36, v229, v36, s[10:11]
	v_cmp_le_i32_e64 s[16:17], 11, v217
	v_cndmask_b32_e64 v37, v229, v37, s[12:13]
	v_cmp_le_i32_e64 s[10:11], 16, v217
	v_cndmask_b32_e64 v38, v229, v38, s[14:15]
	v_cmp_le_i32_e64 s[12:13], 17, v217
	v_cndmask_b32_e64 v39, v229, v39, s[16:17]
	v_cmp_le_i32_e64 s[14:15], 18, v217
	v_cndmask_b32_e64 v40, v229, v40, s[10:11]
	v_cmp_le_i32_e64 s[16:17], 19, v217
	v_cndmask_b32_e64 v41, v229, v41, s[12:13]
	v_cmp_le_i32_e64 s[10:11], 24, v217
	v_cndmask_b32_e64 v42, v229, v42, s[14:15]
	v_cmp_le_i32_e64 s[12:13], 25, v217
	v_cndmask_b32_e64 v43, v229, v43, s[16:17]
	v_cmp_le_i32_e64 s[14:15], 26, v217
	v_cndmask_b32_e64 v44, v229, v44, s[10:11]
	v_cmp_le_i32_e64 s[16:17], 27, v217
	v_cndmask_b32_e64 v45, v229, v45, s[12:13]
	v_cndmask_b32_e64 v46, v229, v46, s[14:15]
	v_cndmask_b32_e64 v47, v229, v47, s[16:17]
	v_max3_f32 v152, v32, v33, v34
	v_max3_f32 v152, v152, v35, v36
	v_max3_f32 v152, v152, v37, v38
	v_max3_f32 v152, v152, v39, v40
	v_max3_f32 v152, v152, v41, v42
	v_max3_f32 v152, v152, v43, v44
	v_max3_f32 v152, v152, v45, v46
	v_max_f32_e32 v152, v152, v47
	v_mov_b32_e32 v218, v152
	s_nop 1
	v_permlane32_swap_b32_e32 v152, v218
	v_max_f32_e32 v152, v152, v218
	v_cmp_lt_f32_e32 vcc, s1, v152
	s_cbranch_vccnz .Lm1h_p0_rare
	v_add_u32_e32 v217, 0x10300, v215
	ds_read_b64_tr_b16 v[48:49], v217
	ds_read_b64_tr_b16 v[50:51], v217 offset:512
	ds_read_b64_tr_b16 v[52:53], v217 offset:4096
	ds_read_b64_tr_b16 v[54:55], v217 offset:4608
	ds_read_b64_tr_b16 v[56:57], v217 offset:1024
	ds_read_b64_tr_b16 v[58:59], v217 offset:1536
	ds_read_b64_tr_b16 v[60:61], v217 offset:5120
	ds_read_b64_tr_b16 v[62:63], v217 offset:5632
	v_exp_f32_e32 v32, v32
	v_exp_f32_e32 v33, v33
	v_exp_f32_e32 v34, v34
	v_exp_f32_e32 v35, v35
	v_exp_f32_e32 v36, v36
	v_exp_f32_e32 v37, v37
	v_exp_f32_e32 v38, v38
	v_exp_f32_e32 v39, v39
	v_exp_f32_e32 v40, v40
	v_exp_f32_e32 v41, v41
	v_exp_f32_e32 v42, v42
	v_exp_f32_e32 v43, v43
	v_exp_f32_e32 v44, v44
	v_exp_f32_e32 v45, v45
	v_exp_f32_e32 v46, v46
	v_exp_f32_e32 v47, v47
	s_nop 0
	v_pk_add_f32 v[222:223], v[34:35], v[38:39]
	v_pk_add_f32 v[224:225], v[32:33], v[36:37]
	v_cvt_pk_bf16_f32 v218, v32, v33
	v_cvt_pk_bf16_f32 v219, v34, v35
	v_cvt_pk_bf16_f32 v220, v36, v37
	v_cvt_pk_bf16_f32 v221, v38, v39
	v_pk_add_f32 v[224:225], v[40:41], v[224:225]
	v_pk_add_f32 v[222:223], v[42:43], v[222:223]
	s_waitcnt lgkmcnt(6)
	v_mfma_f32_32x32x16_bf16 v[16:31], v[218:221], v[48:51], v[16:31]
	v_pk_add_f32 v[224:225], v[44:45], v[224:225]
	v_pk_add_f32 v[222:223], v[46:47], v[222:223]
	s_waitcnt lgkmcnt(4)
	v_mfma_f32_32x32x16_bf16 v[0:15], v[218:221], v[52:55], v[0:15]
	v_cvt_pk_bf16_f32 v232, v40, v41
	v_cvt_pk_bf16_f32 v233, v42, v43
	v_cvt_pk_bf16_f32 v234, v44, v45
	v_cvt_pk_bf16_f32 v235, v46, v47
	v_add_f32_e32 v224, v225, v224
	v_add_f32_e32 v222, v222, v223
	s_waitcnt lgkmcnt(2)
	v_mfma_f32_32x32x16_bf16 v[16:31], v[232:235], v[56:59], v[16:31]
	v_add_f32_e32 v224, v224, v222
	v_add_f32_e32 v151, v151, v224
	s_add_i32 s90, s90, 1
	s_add_i32 s92, s92, 64
	s_sub_i32 s93, s93, 64
	s_waitcnt lgkmcnt(0)
	v_mfma_f32_32x32x16_bf16 v[0:15], v[232:235], v[60:63], v[0:15]
	v_add_u32_e32 v215, 0x2000, v215
	v_add_u32_e32 v216, 0x2080, v216
	s_cmp_lt_i32 s90, s91
	s_cbranch_scc0 .LBB0_402
	s_branch .LBB0_393
.Lm1h_p0_rare:
	v_mov_b32_e32 v48, v229
	v_mov_b32_e32 v49, v229
	v_mov_b32_e32 v50, v229
	v_mov_b32_e32 v51, v229
	v_mov_b32_e32 v52, v229
	v_mov_b32_e32 v53, v229
	v_mov_b32_e32 v54, v229
	v_mov_b32_e32 v55, v229
	v_mov_b32_e32 v56, v229
	v_mov_b32_e32 v57, v229
	v_mov_b32_e32 v58, v229
	v_mov_b32_e32 v59, v229
	v_mov_b32_e32 v60, v229
	v_mov_b32_e32 v61, v229
	v_mov_b32_e32 v62, v229
	v_mov_b32_e32 v63, v229
	s_branch .Lm1_old400
.Lm1h_p1:
	ds_read_b128 v[32:35], v216 offset:512
	ds_read_b128 v[36:39], v216 offset:2592
	ds_read_b128 v[40:43], v216 offset:4672
	ds_read_b128 v[44:47], v216 offset:6752
	s_waitcnt lgkmcnt(3)
	v_mfma_f32_32x32x16_bf16 v[48:63], v[32:35], v[140:143], 0
	s_waitcnt lgkmcnt(2)
	v_mfma_f32_32x32x16_bf16 v[48:63], v[36:39], v[136:139], v[48:63]
	s_waitcnt lgkmcnt(1)
	v_mfma_f32_32x32x16_bf16 v[48:63], v[40:43], v[132:135], v[48:63]
	s_waitcnt lgkmcnt(0)
	v_mfma_f32_32x32x16_bf16 v[48:63], v[44:47], v[128:131], v[48:63]
	v_add_u32_e32 v217, s92, v156
	v_subrev_u32_e32 v217, 63, v217
	v_sub_u32_e32 v217, v214, v217
	s_nop 8
	v_cmp_ge_i32_e64 s[10:11], 32, v217
	v_cmp_ge_i32_e64 s[12:13], 33, v217
	v_cmp_ge_i32_e64 s[14:15], 34, v217
	v_cndmask_b32_e64 v48, v229, v48, s[10:11]
	v_cmp_ge_i32_e64 s[16:17], 35, v217
	v_cndmask_b32_e64 v49, v229, v49, s[12:13]
	v_cmp_ge_i32_e64 s[10:11], 40, v217
	v_cndmask_b32_e64 v50, v229, v50, s[14:15]
	v_cmp_ge_i32_e64 s[12:13], 41, v217
	v_cndmask_b32_e64 v51, v229, v51, s[16:17]
	v_cmp_ge_i32_e64 s[14:15], 42, v217
	v_cndmask_b32_e64 v52, v229, v52, s[10:11]
	v_cmp_ge_i32_e64 s[16:17], 43, v217
	v_cndmask_b32_e64 v53, v229, v53, s[12:13]
	v_cmp_ge_i32_e64 s[10:11], 48, v217
	v_cndmask_b32_e64 v54, v229, v54, s[14:15]
	v_cmp_ge_i32_e64 s[12:13], 49, v217
	v_cndmask_b32_e64 v55, v229, v55, s[16:17]
	v_cmp_ge_i32_e64 s[14:15], 50, v217
	v_cndmask_b32_e64 v56, v229, v56, s[10:11]
	v_cmp_ge_i32_e64 s[16:17], 51, v217
	v_cndmask_b32_e64 v57, v229, v57, s[12:13]
	v_cmp_ge_i32_e64 s[10:11], 56, v217
	v_cndmask_b32_e64 v58, v229, v58, s[14:15]
	v_cmp_ge_i32_e64 s[12:13], 57, v217
	v_cndmask_b32_e64 v59, v229, v59, s[16:17]
	v_cmp_ge_i32_e64 s[14:15], 58, v217
	v_cndmask_b32_e64 v60, v229, v60, s[10:11]
	v_cmp_ge_i32_e64 s[16:17], 59, v217
	v_cndmask_b32_e64 v61, v229, v61, s[12:13]
	v_cndmask_b32_e64 v62, v229, v62, s[14:15]
	v_cndmask_b32_e64 v63, v229, v63, s[16:17]
	v_max3_f32 v152, v48, v49, v50
	v_max3_f32 v152, v152, v51, v52
	v_max3_f32 v152, v152, v53, v54
	v_max3_f32 v152, v152, v55, v56
	v_max3_f32 v152, v152, v57, v58
	v_max3_f32 v152, v152, v59, v60
	v_max3_f32 v152, v152, v61, v62
	v_max_f32_e32 v152, v152, v63
	v_mov_b32_e32 v218, v152
	s_nop 1
	v_permlane32_swap_b32_e32 v152, v218
	v_max_f32_e32 v152, v152, v218
	v_cmp_lt_f32_e32 vcc, s1, v152
	s_cbranch_vccnz .Lm1h_p1_rare
	v_add_u32_e32 v217, 0x10300, v215
	ds_read_b64_tr_b16 v[32:33], v217 offset:2048
	ds_read_b64_tr_b16 v[34:35], v217 offset:2560
	ds_read_b64_tr_b16 v[36:37], v217 offset:6144
	ds_read_b64_tr_b16 v[38:39], v217 offset:6656
	ds_read_b64_tr_b16 v[40:41], v217 offset:3072
	ds_read_b64_tr_b16 v[42:43], v217 offset:3584
	ds_read_b64_tr_b16 v[44:45], v217 offset:7168
	ds_read_b64_tr_b16 v[46:47], v217 offset:7680
	v_exp_f32_e32 v48, v48
	v_exp_f32_e32 v49, v49
	v_exp_f32_e32 v50, v50
	v_exp_f32_e32 v51, v51
	v_exp_f32_e32 v52, v52
	v_exp_f32_e32 v53, v53
	v_exp_f32_e32 v54, v54
	v_exp_f32_e32 v55, v55
	v_exp_f32_e32 v56, v56
	v_exp_f32_e32 v57, v57
	v_exp_f32_e32 v58, v58
	v_exp_f32_e32 v59, v59
	v_exp_f32_e32 v60, v60
	v_exp_f32_e32 v61, v61
	v_exp_f32_e32 v62, v62
	v_exp_f32_e32 v63, v63
	s_nop 0
	v_pk_add_f32 v[222:223], v[50:51], v[54:55]
	v_pk_add_f32 v[224:225], v[48:49], v[52:53]
	v_cvt_pk_bf16_f32 v218, v48, v49
	v_cvt_pk_bf16_f32 v219, v50, v51
	v_cvt_pk_bf16_f32 v220, v52, v53
	v_cvt_pk_bf16_f32 v221, v54, v55
	v_pk_add_f32 v[224:225], v[56:57], v[224:225]
	v_pk_add_f32 v[222:223], v[58:59], v[222:223]
	s_waitcnt lgkmcnt(6)
	v_mfma_f32_32x32x16_bf16 v[16:31], v[218:221], v[32:35], v[16:31]
	v_pk_add_f32 v[224:225], v[60:61], v[224:225]
	v_pk_add_f32 v[222:223], v[62:63], v[222:223]
	s_waitcnt lgkmcnt(4)
	v_mfma_f32_32x32x16_bf16 v[0:15], v[218:221], v[36:39], v[0:15]
	v_cvt_pk_bf16_f32 v232, v56, v57
	v_cvt_pk_bf16_f32 v233, v58, v59
	v_cvt_pk_bf16_f32 v234, v60, v61
	v_cvt_pk_bf16_f32 v235, v62, v63
	v_add_f32_e32 v224, v225, v224
	v_add_f32_e32 v222, v222, v223
	s_waitcnt lgkmcnt(2)
	v_mfma_f32_32x32x16_bf16 v[16:31], v[232:235], v[40:43], v[16:31]
	v_add_f32_e32 v224, v224, v222
	v_add_f32_e32 v151, v151, v224
	s_add_i32 s90, s90, 1
	s_add_i32 s92, s92, 64
	s_sub_i32 s93, s93, 64
	s_waitcnt lgkmcnt(0)
	v_mfma_f32_32x32x16_bf16 v[0:15], v[232:235], v[44:47], v[0:15]
	v_add_u32_e32 v215, 0x2000, v215
	v_add_u32_e32 v216, 0x2080, v216
	s_cmp_lt_i32 s90, s91
	s_cbranch_scc0 .LBB0_402
	s_branch .LBB0_393
.Lm1h_p1_rare:
	v_mov_b32_e32 v32, v229
	v_mov_b32_e32 v33, v229
	v_mov_b32_e32 v34, v229
	v_mov_b32_e32 v35, v229
	v_mov_b32_e32 v36, v229
	v_mov_b32_e32 v37, v229
	v_mov_b32_e32 v38, v229
	v_mov_b32_e32 v39, v229
	v_mov_b32_e32 v40, v229
	v_mov_b32_e32 v41, v229
	v_mov_b32_e32 v42, v229
	v_mov_b32_e32 v43, v229
	v_mov_b32_e32 v44, v229
	v_mov_b32_e32 v45, v229
	v_mov_b32_e32 v46, v229
	v_mov_b32_e32 v47, v229
	s_branch .Lm1_old400
.Lmk_up_0a:
	v_add_u32_e32 v154, s82, v172
	v_sub_u32_e32 v154, v65, v154
	v_cmp_le_i32_e64 s[6:7], 0, v154
	v_cmp_le_i32_e64 s[8:9], 1, v154
	v_cmp_le_i32_e64 s[10:11], 2, v154
	v_cndmask_b32_e64 v32, v229, v32, s[6:7]
	v_cmp_le_i32_e64 s[12:13], 3, v154
	v_cndmask_b32_e64 v33, v229, v33, s[8:9]
	v_cmp_le_i32_e64 s[6:7], 8, v154
	v_cndmask_b32_e64 v34, v229, v34, s[10:11]
	v_cmp_le_i32_e64 s[8:9], 9, v154
	v_cndmask_b32_e64 v35, v229, v35, s[12:13]
	v_cmp_le_i32_e64 s[10:11], 10, v154
	v_cndmask_b32_e64 v36, v229, v36, s[6:7]
	v_cmp_le_i32_e64 s[12:13], 11, v154
	v_cndmask_b32_e64 v37, v229, v37, s[8:9]
	v_cmp_le_i32_e64 s[6:7], 16, v154
	v_cndmask_b32_e64 v38, v229, v38, s[10:11]
	v_cmp_le_i32_e64 s[8:9], 17, v154
	v_cndmask_b32_e64 v39, v229, v39, s[12:13]
	v_cmp_le_i32_e64 s[10:11], 18, v154
	v_cndmask_b32_e64 v40, v229, v40, s[6:7]
	v_cmp_le_i32_e64 s[12:13], 19, v154
	v_cndmask_b32_e64 v41, v229, v41, s[8:9]
	v_cmp_le_i32_e64 s[6:7], 24, v154
	v_cndmask_b32_e64 v42, v229, v42, s[10:11]
	v_cmp_le_i32_e64 s[8:9], 25, v154
	v_cndmask_b32_e64 v43, v229, v43, s[12:13]
	v_cmp_le_i32_e64 s[10:11], 26, v154
	v_cndmask_b32_e64 v44, v229, v44, s[6:7]
	v_cmp_le_i32_e64 s[12:13], 27, v154
	v_cndmask_b32_e64 v45, v229, v45, s[8:9]
	v_cmp_le_i32_e64 s[6:7], 32, v154
	v_cndmask_b32_e64 v46, v229, v46, s[10:11]
	v_cmp_le_i32_e64 s[8:9], 33, v154
	v_cndmask_b32_e64 v47, v229, v47, s[12:13]
	v_cmp_le_i32_e64 s[10:11], 34, v154
	v_cndmask_b32_e64 v48, v229, v48, s[6:7]
	v_cmp_le_i32_e64 s[12:13], 35, v154
	v_cndmask_b32_e64 v49, v229, v49, s[8:9]
	v_cmp_le_i32_e64 s[6:7], 40, v154
	v_cndmask_b32_e64 v50, v229, v50, s[10:11]
	v_cmp_le_i32_e64 s[8:9], 41, v154
	v_cndmask_b32_e64 v51, v229, v51, s[12:13]
	v_cmp_le_i32_e64 s[10:11], 42, v154
	v_cndmask_b32_e64 v52, v229, v52, s[6:7]
	v_cmp_le_i32_e64 s[12:13], 43, v154
	v_cndmask_b32_e64 v53, v229, v53, s[8:9]
	v_cmp_le_i32_e64 s[6:7], 48, v154
	v_cndmask_b32_e64 v54, v229, v54, s[10:11]
	v_cmp_le_i32_e64 s[8:9], 49, v154
	v_cndmask_b32_e64 v55, v229, v55, s[12:13]
	v_cmp_le_i32_e64 s[10:11], 50, v154
	v_cndmask_b32_e64 v56, v229, v56, s[6:7]
	v_cmp_le_i32_e64 s[12:13], 51, v154
	v_cndmask_b32_e64 v57, v229, v57, s[8:9]
	v_cmp_le_i32_e64 s[6:7], 56, v154
	v_cndmask_b32_e64 v58, v229, v58, s[10:11]
	v_cmp_le_i32_e64 s[8:9], 57, v154
	v_cndmask_b32_e64 v59, v229, v59, s[12:13]
	v_cmp_le_i32_e64 s[10:11], 58, v154
	v_cndmask_b32_e64 v60, v229, v60, s[6:7]
	v_cmp_le_i32_e64 s[12:13], 59, v154
	v_cndmask_b32_e64 v61, v229, v61, s[8:9]
	v_cndmask_b32_e64 v62, v229, v62, s[10:11]
	v_cndmask_b32_e64 v63, v229, v63, s[12:13]
	s_branch .LBB0_470
.Lmk_lo_0a:
	v_add_u32_e32 v154, s82, v172
	v_sub_u32_e32 v154, v167, v154
	v_cmp_ge_i32_e64 s[6:7], 0, v154
	v_cmp_ge_i32_e64 s[8:9], 1, v154
	v_cmp_ge_i32_e64 s[10:11], 2, v154
	v_cndmask_b32_e64 v32, v229, v32, s[6:7]
	v_cmp_ge_i32_e64 s[12:13], 3, v154
	v_cndmask_b32_e64 v33, v229, v33, s[8:9]
	v_cmp_ge_i32_e64 s[6:7], 8, v154
	v_cndmask_b32_e64 v34, v229, v34, s[10:11]
	v_cmp_ge_i32_e64 s[8:9], 9, v154
	v_cndmask_b32_e64 v35, v229, v35, s[12:13]
	v_cmp_ge_i32_e64 s[10:11], 10, v154
	v_cndmask_b32_e64 v36, v229, v36, s[6:7]
	v_cmp_ge_i32_e64 s[12:13], 11, v154
	v_cndmask_b32_e64 v37, v229, v37, s[8:9]
	v_cmp_ge_i32_e64 s[6:7], 16, v154
	v_cndmask_b32_e64 v38, v229, v38, s[10:11]
	v_cmp_ge_i32_e64 s[8:9], 17, v154
	v_cndmask_b32_e64 v39, v229, v39, s[12:13]
	v_cmp_ge_i32_e64 s[10:11], 18, v154
	v_cndmask_b32_e64 v40, v229, v40, s[6:7]
	v_cmp_ge_i32_e64 s[12:13], 19, v154
	v_cndmask_b32_e64 v41, v229, v41, s[8:9]
	v_cmp_ge_i32_e64 s[6:7], 24, v154
	v_cndmask_b32_e64 v42, v229, v42, s[10:11]
	v_cmp_ge_i32_e64 s[8:9], 25, v154
	v_cndmask_b32_e64 v43, v229, v43, s[12:13]
	v_cmp_ge_i32_e64 s[10:11], 26, v154
	v_cndmask_b32_e64 v44, v229, v44, s[6:7]
	v_cmp_ge_i32_e64 s[12:13], 27, v154
	v_cndmask_b32_e64 v45, v229, v45, s[8:9]
	v_cmp_ge_i32_e64 s[6:7], 32, v154
	v_cndmask_b32_e64 v46, v229, v46, s[10:11]
	v_cmp_ge_i32_e64 s[8:9], 33, v154
	v_cndmask_b32_e64 v47, v229, v47, s[12:13]
	v_cmp_ge_i32_e64 s[10:11], 34, v154
	v_cndmask_b32_e64 v48, v229, v48, s[6:7]
	v_cmp_ge_i32_e64 s[12:13], 35, v154
	v_cndmask_b32_e64 v49, v229, v49, s[8:9]
	v_cmp_ge_i32_e64 s[6:7], 40, v154
	v_cndmask_b32_e64 v50, v229, v50, s[10:11]
	v_cmp_ge_i32_e64 s[8:9], 41, v154
	v_cndmask_b32_e64 v51, v229, v51, s[12:13]
	v_cmp_ge_i32_e64 s[10:11], 42, v154
	v_cndmask_b32_e64 v52, v229, v52, s[6:7]
	v_cmp_ge_i32_e64 s[12:13], 43, v154
	v_cndmask_b32_e64 v53, v229, v53, s[8:9]
	v_cmp_ge_i32_e64 s[6:7], 48, v154
	v_cndmask_b32_e64 v54, v229, v54, s[10:11]
	v_cmp_ge_i32_e64 s[8:9], 49, v154
	v_cndmask_b32_e64 v55, v229, v55, s[12:13]
	v_cmp_ge_i32_e64 s[10:11], 50, v154
	v_cndmask_b32_e64 v56, v229, v56, s[6:7]
	v_cmp_ge_i32_e64 s[12:13], 51, v154
	v_cndmask_b32_e64 v57, v229, v57, s[8:9]
	v_cmp_ge_i32_e64 s[6:7], 56, v154
	v_cndmask_b32_e64 v58, v229, v58, s[10:11]
	v_cmp_ge_i32_e64 s[8:9], 57, v154
	v_cndmask_b32_e64 v59, v229, v59, s[12:13]
	v_cmp_ge_i32_e64 s[10:11], 58, v154
	v_cndmask_b32_e64 v60, v229, v60, s[6:7]
	v_cmp_ge_i32_e64 s[12:13], 59, v154
	v_cndmask_b32_e64 v61, v229, v61, s[8:9]
	v_cndmask_b32_e64 v62, v229, v62, s[10:11]
	v_cndmask_b32_e64 v63, v229, v63, s[12:13]
	s_branch .LBB0_470
.Lmk_up_0b:
	v_add_u32_e32 v154, s82, v172
	v_add_u32_e32 v154, 64, v154
	v_sub_u32_e32 v154, v65, v154
	v_cmp_le_i32_e64 s[6:7], 0, v154
	v_cmp_le_i32_e64 s[8:9], 1, v154
	v_cmp_le_i32_e64 s[10:11], 2, v154
	v_cndmask_b32_e64 v66, v229, v66, s[6:7]
	v_cmp_le_i32_e64 s[12:13], 3, v154
	v_cndmask_b32_e64 v67, v229, v67, s[8:9]
	v_cmp_le_i32_e64 s[6:7], 8, v154
	v_cndmask_b32_e64 v68, v229, v68, s[10:11]
	v_cmp_le_i32_e64 s[8:9], 9, v154
	v_cndmask_b32_e64 v69, v229, v69, s[12:13]
	v_cmp_le_i32_e64 s[10:11], 10, v154
	v_cndmask_b32_e64 v70, v229, v70, s[6:7]
	v_cmp_le_i32_e64 s[12:13], 11, v154
	v_cndmask_b32_e64 v71, v229, v71, s[8:9]
	v_cmp_le_i32_e64 s[6:7], 16, v154
	v_cndmask_b32_e64 v72, v229, v72, s[10:11]
	v_cmp_le_i32_e64 s[8:9], 17, v154
	v_cndmask_b32_e64 v73, v229, v73, s[12:13]
	v_cmp_le_i32_e64 s[10:11], 18, v154
	v_cndmask_b32_e64 v74, v229, v74, s[6:7]
	v_cmp_le_i32_e64 s[12:13], 19, v154
	v_cndmask_b32_e64 v75, v229, v75, s[8:9]
	v_cmp_le_i32_e64 s[6:7], 24, v154
	v_cndmask_b32_e64 v76, v229, v76, s[10:11]
	v_cmp_le_i32_e64 s[8:9], 25, v154
	v_cndmask_b32_e64 v77, v229, v77, s[12:13]
	v_cmp_le_i32_e64 s[10:11], 26, v154
	v_cndmask_b32_e64 v78, v229, v78, s[6:7]
	v_cmp_le_i32_e64 s[12:13], 27, v154
	v_cndmask_b32_e64 v79, v229, v79, s[8:9]
	v_cmp_le_i32_e64 s[6:7], 32, v154
	v_cndmask_b32_e64 v80, v229, v80, s[10:11]
	v_cmp_le_i32_e64 s[8:9], 33, v154
	v_cndmask_b32_e64 v81, v229, v81, s[12:13]
	v_cmp_le_i32_e64 s[10:11], 34, v154
	v_cndmask_b32_e64 v82, v229, v82, s[6:7]
	v_cmp_le_i32_e64 s[12:13], 35, v154
	v_cndmask_b32_e64 v83, v229, v83, s[8:9]
	v_cmp_le_i32_e64 s[6:7], 40, v154
	v_cndmask_b32_e64 v84, v229, v84, s[10:11]
	v_cmp_le_i32_e64 s[8:9], 41, v154
	v_cndmask_b32_e64 v85, v229, v85, s[12:13]
	v_cmp_le_i32_e64 s[10:11], 42, v154
	v_cndmask_b32_e64 v86, v229, v86, s[6:7]
	v_cmp_le_i32_e64 s[12:13], 43, v154
	v_cndmask_b32_e64 v87, v229, v87, s[8:9]
	v_cmp_le_i32_e64 s[6:7], 48, v154
	v_cndmask_b32_e64 v88, v229, v88, s[10:11]
	v_cmp_le_i32_e64 s[8:9], 49, v154
	v_cndmask_b32_e64 v89, v229, v89, s[12:13]
	v_cmp_le_i32_e64 s[10:11], 50, v154
	v_cndmask_b32_e64 v90, v229, v90, s[6:7]
	v_cmp_le_i32_e64 s[12:13], 51, v154
	v_cndmask_b32_e64 v91, v229, v91, s[8:9]
	v_cmp_le_i32_e64 s[6:7], 56, v154
	v_cndmask_b32_e64 v92, v229, v92, s[10:11]
	v_cmp_le_i32_e64 s[8:9], 57, v154
	v_cndmask_b32_e64 v93, v229, v93, s[12:13]
	v_cmp_le_i32_e64 s[10:11], 58, v154
	v_cndmask_b32_e64 v94, v229, v94, s[6:7]
	v_cmp_le_i32_e64 s[12:13], 59, v154
	v_cndmask_b32_e64 v95, v229, v95, s[8:9]
	v_cndmask_b32_e64 v96, v229, v96, s[10:11]
	v_cndmask_b32_e64 v97, v229, v97, s[12:13]
	s_branch .LBB0_483
.Lmk_lo_0b:
	v_add_u32_e32 v154, s82, v172
	v_add_u32_e32 v154, 64, v154
	v_sub_u32_e32 v154, v167, v154
	v_cmp_ge_i32_e64 s[6:7], 0, v154
	v_cmp_ge_i32_e64 s[8:9], 1, v154
	v_cmp_ge_i32_e64 s[10:11], 2, v154
	v_cndmask_b32_e64 v66, v229, v66, s[6:7]
	v_cmp_ge_i32_e64 s[12:13], 3, v154
	v_cndmask_b32_e64 v67, v229, v67, s[8:9]
	v_cmp_ge_i32_e64 s[6:7], 8, v154
	v_cndmask_b32_e64 v68, v229, v68, s[10:11]
	v_cmp_ge_i32_e64 s[8:9], 9, v154
	v_cndmask_b32_e64 v69, v229, v69, s[12:13]
	v_cmp_ge_i32_e64 s[10:11], 10, v154
	v_cndmask_b32_e64 v70, v229, v70, s[6:7]
	v_cmp_ge_i32_e64 s[12:13], 11, v154
	v_cndmask_b32_e64 v71, v229, v71, s[8:9]
	v_cmp_ge_i32_e64 s[6:7], 16, v154
	v_cndmask_b32_e64 v72, v229, v72, s[10:11]
	v_cmp_ge_i32_e64 s[8:9], 17, v154
	v_cndmask_b32_e64 v73, v229, v73, s[12:13]
	v_cmp_ge_i32_e64 s[10:11], 18, v154
	v_cndmask_b32_e64 v74, v229, v74, s[6:7]
	v_cmp_ge_i32_e64 s[12:13], 19, v154
	v_cndmask_b32_e64 v75, v229, v75, s[8:9]
	v_cmp_ge_i32_e64 s[6:7], 24, v154
	v_cndmask_b32_e64 v76, v229, v76, s[10:11]
	v_cmp_ge_i32_e64 s[8:9], 25, v154
	v_cndmask_b32_e64 v77, v229, v77, s[12:13]
	v_cmp_ge_i32_e64 s[10:11], 26, v154
	v_cndmask_b32_e64 v78, v229, v78, s[6:7]
	v_cmp_ge_i32_e64 s[12:13], 27, v154
	v_cndmask_b32_e64 v79, v229, v79, s[8:9]
	v_cmp_ge_i32_e64 s[6:7], 32, v154
	v_cndmask_b32_e64 v80, v229, v80, s[10:11]
	v_cmp_ge_i32_e64 s[8:9], 33, v154
	v_cndmask_b32_e64 v81, v229, v81, s[12:13]
	v_cmp_ge_i32_e64 s[10:11], 34, v154
	v_cndmask_b32_e64 v82, v229, v82, s[6:7]
	v_cmp_ge_i32_e64 s[12:13], 35, v154
	v_cndmask_b32_e64 v83, v229, v83, s[8:9]
	v_cmp_ge_i32_e64 s[6:7], 40, v154
	v_cndmask_b32_e64 v84, v229, v84, s[10:11]
	v_cmp_ge_i32_e64 s[8:9], 41, v154
	v_cndmask_b32_e64 v85, v229, v85, s[12:13]
	v_cmp_ge_i32_e64 s[10:11], 42, v154
	v_cndmask_b32_e64 v86, v229, v86, s[6:7]
	v_cmp_ge_i32_e64 s[12:13], 43, v154
	v_cndmask_b32_e64 v87, v229, v87, s[8:9]
	v_cmp_ge_i32_e64 s[6:7], 48, v154
	v_cndmask_b32_e64 v88, v229, v88, s[10:11]
	v_cmp_ge_i32_e64 s[8:9], 49, v154
	v_cndmask_b32_e64 v89, v229, v89, s[12:13]
	v_cmp_ge_i32_e64 s[10:11], 50, v154
	v_cndmask_b32_e64 v90, v229, v90, s[6:7]
	v_cmp_ge_i32_e64 s[12:13], 51, v154
	v_cndmask_b32_e64 v91, v229, v91, s[8:9]
	v_cmp_ge_i32_e64 s[6:7], 56, v154
	v_cndmask_b32_e64 v92, v229, v92, s[10:11]
	v_cmp_ge_i32_e64 s[8:9], 57, v154
	v_cndmask_b32_e64 v93, v229, v93, s[12:13]
	v_cmp_ge_i32_e64 s[10:11], 58, v154
	v_cndmask_b32_e64 v94, v229, v94, s[6:7]
	v_cmp_ge_i32_e64 s[12:13], 59, v154
	v_cndmask_b32_e64 v95, v229, v95, s[8:9]
	v_cndmask_b32_e64 v96, v229, v96, s[10:11]
	v_cndmask_b32_e64 v97, v229, v97, s[12:13]
	s_branch .LBB0_483
.Lmk_up_1:
	s_nop 7
	v_add_u32_e32 v152, s92, v156
	v_subrev_u32_e32 v152, 63, v152
	v_sub_u32_e32 v152, v213, v152
	v_cmp_le_i32_e64 s[10:11], 0, v152
	v_cmp_le_i32_e64 s[12:13], 1, v152
	v_cmp_le_i32_e64 s[14:15], 2, v152
	v_cndmask_b32_e64 v32, v229, v32, s[10:11]
	v_cmp_le_i32_e64 s[16:17], 3, v152
	v_cndmask_b32_e64 v33, v229, v33, s[12:13]
	v_cmp_le_i32_e64 s[10:11], 8, v152
	v_cndmask_b32_e64 v34, v229, v34, s[14:15]
	v_cmp_le_i32_e64 s[12:13], 9, v152
	v_cndmask_b32_e64 v35, v229, v35, s[16:17]
	v_cmp_le_i32_e64 s[14:15], 10, v152
	v_cndmask_b32_e64 v36, v229, v36, s[10:11]
	v_cmp_le_i32_e64 s[16:17], 11, v152
	v_cndmask_b32_e64 v37, v229, v37, s[12:13]
	v_cmp_le_i32_e64 s[10:11], 16, v152
	v_cndmask_b32_e64 v38, v229, v38, s[14:15]
	v_cmp_le_i32_e64 s[12:13], 17, v152
	v_cndmask_b32_e64 v39, v229, v39, s[16:17]
	v_cmp_le_i32_e64 s[14:15], 18, v152
	v_cndmask_b32_e64 v40, v229, v40, s[10:11]
	v_cmp_le_i32_e64 s[16:17], 19, v152
	v_cndmask_b32_e64 v41, v229, v41, s[12:13]
	v_cmp_le_i32_e64 s[10:11], 24, v152
	v_cndmask_b32_e64 v42, v229, v42, s[14:15]
	v_cmp_le_i32_e64 s[12:13], 25, v152
	v_cndmask_b32_e64 v43, v229, v43, s[16:17]
	v_cmp_le_i32_e64 s[14:15], 26, v152
	v_cndmask_b32_e64 v44, v229, v44, s[10:11]
	v_cmp_le_i32_e64 s[16:17], 27, v152
	v_cndmask_b32_e64 v45, v229, v45, s[12:13]
	v_cmp_le_i32_e64 s[10:11], 32, v152
	v_cndmask_b32_e64 v46, v229, v46, s[14:15]
	v_cmp_le_i32_e64 s[12:13], 33, v152
	v_cndmask_b32_e64 v47, v229, v47, s[16:17]
	v_cmp_le_i32_e64 s[14:15], 34, v152
	v_cndmask_b32_e64 v48, v229, v48, s[10:11]
	v_cmp_le_i32_e64 s[16:17], 35, v152
	v_cndmask_b32_e64 v49, v229, v49, s[12:13]
	v_cmp_le_i32_e64 s[10:11], 40, v152
	v_cndmask_b32_e64 v50, v229, v50, s[14:15]
	v_cmp_le_i32_e64 s[12:13], 41, v152
	v_cndmask_b32_e64 v51, v229, v51, s[16:17]
	v_cmp_le_i32_e64 s[14:15], 42, v152
	v_cndmask_b32_e64 v52, v229, v52, s[10:11]
	v_cmp_le_i32_e64 s[16:17], 43, v152
	v_cndmask_b32_e64 v53, v229, v53, s[12:13]
	v_cmp_le_i32_e64 s[10:11], 48, v152
	v_cndmask_b32_e64 v54, v229, v54, s[14:15]
	v_cmp_le_i32_e64 s[12:13], 49, v152
	v_cndmask_b32_e64 v55, v229, v55, s[16:17]
	v_cmp_le_i32_e64 s[14:15], 50, v152
	v_cndmask_b32_e64 v56, v229, v56, s[10:11]
	v_cmp_le_i32_e64 s[16:17], 51, v152
	v_cndmask_b32_e64 v57, v229, v57, s[12:13]
	v_cmp_le_i32_e64 s[10:11], 56, v152
	v_cndmask_b32_e64 v58, v229, v58, s[14:15]
	v_cmp_le_i32_e64 s[12:13], 57, v152
	v_cndmask_b32_e64 v59, v229, v59, s[16:17]
	v_cmp_le_i32_e64 s[14:15], 58, v152
	v_cndmask_b32_e64 v60, v229, v60, s[10:11]
	v_cmp_le_i32_e64 s[16:17], 59, v152
	v_cndmask_b32_e64 v61, v229, v61, s[12:13]
	v_cndmask_b32_e64 v62, v229, v62, s[14:15]
	v_cndmask_b32_e64 v63, v229, v63, s[16:17]
	s_branch .LBB0_399
.Lmk_lo_1:
	s_nop 7
	v_add_u32_e32 v152, s92, v156
	v_subrev_u32_e32 v152, 63, v152
	v_sub_u32_e32 v152, v214, v152
	v_cmp_ge_i32_e64 s[10:11], 0, v152
	v_cmp_ge_i32_e64 s[12:13], 1, v152
	v_cmp_ge_i32_e64 s[14:15], 2, v152
	v_cndmask_b32_e64 v32, v229, v32, s[10:11]
	v_cmp_ge_i32_e64 s[16:17], 3, v152
	v_cndmask_b32_e64 v33, v229, v33, s[12:13]
	v_cmp_ge_i32_e64 s[10:11], 8, v152
	v_cndmask_b32_e64 v34, v229, v34, s[14:15]
	v_cmp_ge_i32_e64 s[12:13], 9, v152
	v_cndmask_b32_e64 v35, v229, v35, s[16:17]
	v_cmp_ge_i32_e64 s[14:15], 10, v152
	v_cndmask_b32_e64 v36, v229, v36, s[10:11]
	v_cmp_ge_i32_e64 s[16:17], 11, v152
	v_cndmask_b32_e64 v37, v229, v37, s[12:13]
	v_cmp_ge_i32_e64 s[10:11], 16, v152
	v_cndmask_b32_e64 v38, v229, v38, s[14:15]
	v_cmp_ge_i32_e64 s[12:13], 17, v152
	v_cndmask_b32_e64 v39, v229, v39, s[16:17]
	v_cmp_ge_i32_e64 s[14:15], 18, v152
	v_cndmask_b32_e64 v40, v229, v40, s[10:11]
	v_cmp_ge_i32_e64 s[16:17], 19, v152
	v_cndmask_b32_e64 v41, v229, v41, s[12:13]
	v_cmp_ge_i32_e64 s[10:11], 24, v152
	v_cndmask_b32_e64 v42, v229, v42, s[14:15]
	v_cmp_ge_i32_e64 s[12:13], 25, v152
	v_cndmask_b32_e64 v43, v229, v43, s[16:17]
	v_cmp_ge_i32_e64 s[14:15], 26, v152
	v_cndmask_b32_e64 v44, v229, v44, s[10:11]
	v_cmp_ge_i32_e64 s[16:17], 27, v152
	v_cndmask_b32_e64 v45, v229, v45, s[12:13]
	v_cmp_ge_i32_e64 s[10:11], 32, v152
	v_cndmask_b32_e64 v46, v229, v46, s[14:15]
	v_cmp_ge_i32_e64 s[12:13], 33, v152
	v_cndmask_b32_e64 v47, v229, v47, s[16:17]
	v_cmp_ge_i32_e64 s[14:15], 34, v152
	v_cndmask_b32_e64 v48, v229, v48, s[10:11]
	v_cmp_ge_i32_e64 s[16:17], 35, v152
	v_cndmask_b32_e64 v49, v229, v49, s[12:13]
	v_cmp_ge_i32_e64 s[10:11], 40, v152
	v_cndmask_b32_e64 v50, v229, v50, s[14:15]
	v_cmp_ge_i32_e64 s[12:13], 41, v152
	v_cndmask_b32_e64 v51, v229, v51, s[16:17]
	v_cmp_ge_i32_e64 s[14:15], 42, v152
	v_cndmask_b32_e64 v52, v229, v52, s[10:11]
	v_cmp_ge_i32_e64 s[16:17], 43, v152
	v_cndmask_b32_e64 v53, v229, v53, s[12:13]
	v_cmp_ge_i32_e64 s[10:11], 48, v152
	v_cndmask_b32_e64 v54, v229, v54, s[14:15]
	v_cmp_ge_i32_e64 s[12:13], 49, v152
	v_cndmask_b32_e64 v55, v229, v55, s[16:17]
	v_cmp_ge_i32_e64 s[14:15], 50, v152
	v_cndmask_b32_e64 v56, v229, v56, s[10:11]
	v_cmp_ge_i32_e64 s[16:17], 51, v152
	v_cndmask_b32_e64 v57, v229, v57, s[12:13]
	v_cmp_ge_i32_e64 s[10:11], 56, v152
	v_cndmask_b32_e64 v58, v229, v58, s[14:15]
	v_cmp_ge_i32_e64 s[12:13], 57, v152
	v_cndmask_b32_e64 v59, v229, v59, s[16:17]
	v_cmp_ge_i32_e64 s[14:15], 58, v152
	v_cndmask_b32_e64 v60, v229, v60, s[10:11]
	v_cmp_ge_i32_e64 s[16:17], 59, v152
	v_cndmask_b32_e64 v61, v229, v61, s[12:13]
	v_cndmask_b32_e64 v62, v229, v62, s[14:15]
	v_cndmask_b32_e64 v63, v229, v63, s[16:17]
	s_branch .LBB0_399

.LBB0_466:
	s_add_i32 s6, s82, 63
	s_cmp_le_u32 s6, s96
	s_cselect_b64 s[6:7], -1, 0
	s_cmp_gt_i32 s82, s80
	s_cselect_b64 s[8:9], -1, 0
	s_and_b64 s[10:11], s[6:7], s[8:9]
	s_and_b64 vcc, exec, s[10:11]
	s_cbranch_vccnz .LBB0_470
	s_and_b64 vcc, exec, s[6:7]
	s_cbranch_vccnz .Lmk_lo_0a
	s_and_b64 vcc, exec, s[8:9]
	s_cbranch_vccnz .Lmk_up_0a
	v_add_u32_e32 v154, s82, v172
	v_add_u32_e32 v155, 32, v154
	v_add_u32_e32 v156, 33, v154
	v_cmp_le_u32_e64 s[8:9], v155, v65
	v_cmp_ge_i32_e64 s[10:11], v155, v167
	v_add_u32_e32 v155, 1, v154
	v_cmp_le_u32_e64 s[12:13], v156, v65
	v_cmp_ge_i32_e64 s[14:15], v156, v167
	v_add_u32_e32 v156, 34, v154
	s_and_b64 s[8:9], s[8:9], s[10:11]
	v_cmp_ge_i32_e64 s[10:11], v155, v167
	s_and_b64 s[12:13], s[12:13], s[14:15]
	v_add_u32_e32 v155, 2, v154
	v_cmp_le_u32_e64 s[16:17], v156, v65
	v_cmp_ge_i32_e64 s[18:19], v156, v167
	v_add_u32_e32 v156, 35, v154
	v_cndmask_b32_e64 v49, v229, v49, s[12:13]
	v_cmp_le_u32_e64 s[12:13], v155, v65
	v_cmp_ge_i32_e64 s[14:15], v155, v167
	s_and_b64 s[16:17], s[16:17], s[18:19]
	v_add_u32_e32 v155, 3, v154
	v_cmp_le_u32_e64 s[20:21], v156, v65
	v_cmp_ge_i32_e64 s[22:23], v156, v167
	v_add_u32_e32 v156, 40, v154
	v_cndmask_b32_e64 v50, v229, v50, s[16:17]
	v_cmp_le_u32_e64 s[16:17], v155, v65
	v_cmp_ge_i32_e64 s[18:19], v155, v167
	s_and_b64 s[20:21], s[20:21], s[22:23]
	v_add_u32_e32 v155, 8, v154
	v_cmp_le_u32_e64 s[24:25], v156, v65
	v_cmp_ge_i32_e64 s[26:27], v156, v167
	v_add_u32_e32 v156, 41, v154
	v_cndmask_b32_e64 v51, v229, v51, s[20:21]
	v_cmp_le_u32_e64 s[20:21], v155, v65
	v_cmp_ge_i32_e64 s[22:23], v155, v167
	s_and_b64 s[24:25], s[24:25], s[26:27]
	v_add_u32_e32 v155, 9, v154
	v_cmp_le_u32_e64 s[28:29], v156, v65
	v_cmp_ge_i32_e64 s[30:31], v156, v167
	v_add_u32_e32 v156, 42, v154
	v_cndmask_b32_e64 v52, v229, v52, s[24:25]
	v_cmp_le_u32_e64 s[24:25], v155, v65
	v_cmp_ge_i32_e64 s[26:27], v155, v167
	s_and_b64 s[28:29], s[28:29], s[30:31]
	v_add_u32_e32 v155, 10, v154
	v_cmp_le_u32_e64 s[34:35], v156, v65
	v_cmp_ge_i32_e64 s[36:37], v156, v167
	v_add_u32_e32 v156, 43, v154
	v_cndmask_b32_e64 v53, v229, v53, s[28:29]
	v_cmp_le_u32_e64 s[28:29], v155, v65
	v_cmp_ge_i32_e64 s[30:31], v155, v167
	s_and_b64 s[34:35], s[34:35], s[36:37]
	v_add_u32_e32 v155, 11, v154
	v_cmp_le_u32_e64 s[38:39], v156, v65
	v_cmp_ge_i32_e64 s[40:41], v156, v167
	v_add_u32_e32 v156, 48, v154
	v_cndmask_b32_e64 v54, v229, v54, s[34:35]
	v_cmp_le_u32_e64 s[34:35], v155, v65
	v_cmp_ge_i32_e64 s[36:37], v155, v167
	s_and_b64 s[38:39], s[38:39], s[40:41]
	v_add_u32_e32 v155, 16, v154
	v_cmp_le_u32_e64 s[42:43], v156, v65
	v_cmp_ge_i32_e64 s[44:45], v156, v167
	v_add_u32_e32 v156, 49, v154
	v_cndmask_b32_e64 v55, v229, v55, s[38:39]
	v_cmp_le_u32_e64 s[38:39], v155, v65
	v_cmp_ge_i32_e64 s[40:41], v155, v167
	s_and_b64 s[42:43], s[42:43], s[44:45]
	v_add_u32_e32 v155, 17, v154
	v_cmp_le_u32_e64 s[46:47], v156, v65
	v_cmp_ge_i32_e64 s[48:49], v156, v167
	v_add_u32_e32 v156, 50, v154
	v_cndmask_b32_e64 v56, v229, v56, s[42:43]
	v_cmp_le_u32_e64 s[42:43], v155, v65
	v_cmp_ge_i32_e64 s[44:45], v155, v167
	s_and_b64 s[46:47], s[46:47], s[48:49]
	v_add_u32_e32 v155, 18, v154
	v_cmp_le_u32_e64 s[50:51], v156, v65
	v_cmp_ge_i32_e64 s[52:53], v156, v167
	v_add_u32_e32 v156, 51, v154
	v_cndmask_b32_e64 v57, v229, v57, s[46:47]
	v_cmp_le_u32_e64 s[46:47], v155, v65
	v_cmp_ge_i32_e64 s[48:49], v155, v167
	s_and_b64 s[50:51], s[50:51], s[52:53]
	v_add_u32_e32 v155, 19, v154
	v_cmp_le_u32_e64 s[54:55], v156, v65
	v_cmp_ge_i32_e64 s[56:57], v156, v167
	v_add_u32_e32 v156, 56, v154
	v_cndmask_b32_e64 v58, v229, v58, s[50:51]
	v_cmp_le_u32_e64 s[50:51], v155, v65
	v_cmp_ge_i32_e64 s[52:53], v155, v167
	s_and_b64 s[54:55], s[54:55], s[56:57]
	v_add_u32_e32 v155, 24, v154
	v_cmp_le_u32_e64 s[58:59], v156, v65
	v_cmp_ge_i32_e64 s[60:61], v156, v167
	v_add_u32_e32 v156, 57, v154
	v_cndmask_b32_e64 v59, v229, v59, s[54:55]
	v_cmp_le_u32_e64 s[54:55], v155, v65
	v_cmp_ge_i32_e64 s[56:57], v155, v167
	s_and_b64 s[58:59], s[58:59], s[60:61]
	v_add_u32_e32 v155, 25, v154
	v_cmp_le_u32_e64 s[62:63], v156, v65
	v_cmp_ge_i32_e64 s[64:65], v156, v167
	v_cndmask_b32_e64 v60, v229, v60, s[58:59]
	v_cmp_le_u32_e64 s[58:59], v155, v65
	v_cmp_ge_i32_e64 s[60:61], v155, v167
	s_and_b64 s[62:63], s[62:63], s[64:65]
	v_add_u32_e32 v155, 26, v154
	v_add_u32_e32 v156, 58, v154
	v_cmp_le_u32_e32 vcc, v154, v65
	v_cmp_ge_i32_e64 s[6:7], v154, v167
	v_cndmask_b32_e64 v48, v229, v48, s[8:9]
	v_cmp_lt_u32_e64 s[8:9], v154, v65
	v_cndmask_b32_e64 v61, v229, v61, s[62:63]
	v_cmp_le_u32_e64 s[62:63], v155, v65
	v_cmp_le_u32_e64 s[66:67], v156, v65
	v_cmp_ge_i32_e64 s[64:65], v155, v167
	v_cmp_ge_i32_e64 s[68:69], v156, v167
	v_add_u32_e32 v155, 27, v154
	v_add_u32_e32 v154, 59, v154
	s_and_b64 s[66:67], s[66:67], s[68:69]
	v_cmp_gt_u32_e64 s[70:71], v154, v65
	v_cmp_lt_i32_e64 s[72:73], v154, v167
	v_cndmask_b32_e64 v62, v229, v62, s[66:67]
	v_cmp_le_u32_e64 s[66:67], v155, v65
	v_cmp_ge_i32_e64 s[68:69], v155, v167
	s_or_b64 s[72:73], s[70:71], s[72:73]
	s_and_saveexec_b64 s[70:71], s[72:73]
	v_mov_b32_e32 v63, s0
	s_or_b64 exec, exec, s[70:71]
	s_and_b64 vcc, vcc, s[6:7]
	v_cndmask_b32_e32 v32, v229, v32, vcc
	s_and_b64 vcc, s[8:9], s[10:11]
	v_cndmask_b32_e32 v33, v229, v33, vcc
	s_and_b64 vcc, s[12:13], s[14:15]
	v_cndmask_b32_e32 v34, v229, v34, vcc
	s_and_b64 vcc, s[16:17], s[18:19]
	v_cndmask_b32_e32 v35, v229, v35, vcc
	s_and_b64 vcc, s[20:21], s[22:23]
	v_cndmask_b32_e32 v36, v229, v36, vcc
	s_and_b64 vcc, s[24:25], s[26:27]
	v_cndmask_b32_e32 v37, v229, v37, vcc
	s_and_b64 vcc, s[28:29], s[30:31]
	v_cndmask_b32_e32 v38, v229, v38, vcc
	s_and_b64 vcc, s[34:35], s[36:37]
	v_cndmask_b32_e32 v39, v229, v39, vcc
	s_and_b64 vcc, s[38:39], s[40:41]
	v_cndmask_b32_e32 v40, v229, v40, vcc
	s_and_b64 vcc, s[42:43], s[44:45]
	v_cndmask_b32_e32 v41, v229, v41, vcc
	s_and_b64 vcc, s[46:47], s[48:49]
	v_cndmask_b32_e32 v42, v229, v42, vcc
	s_and_b64 vcc, s[50:51], s[52:53]
	v_cndmask_b32_e32 v43, v229, v43, vcc
	s_and_b64 vcc, s[54:55], s[56:57]
	v_cndmask_b32_e32 v44, v229, v44, vcc
	s_and_b64 vcc, s[58:59], s[60:61]
	v_cndmask_b32_e32 v45, v229, v45, vcc
	s_and_b64 vcc, s[62:63], s[64:65]
	v_cndmask_b32_e32 v46, v229, v46, vcc
	s_and_b64 vcc, s[66:67], s[68:69]
	v_cndmask_b32_e32 v47, v229, v47, vcc

.LBB0_479:
	s_add_i32 s8, s82, 64
	s_add_i32 s6, s82, 0x7f
	s_cmp_le_u32 s6, s96
	s_cselect_b64 s[6:7], -1, 0
	s_cmp_gt_i32 s8, s80
	s_cselect_b64 s[8:9], -1, 0
	s_and_b64 s[10:11], s[6:7], s[8:9]
	s_and_b64 vcc, exec, s[10:11]
	s_cbranch_vccnz .LBB0_483
	s_and_b64 vcc, exec, s[6:7]
	s_cbranch_vccnz .Lmk_lo_0b
	s_and_b64 vcc, exec, s[8:9]
	s_cbranch_vccnz .Lmk_up_0b
	v_add_u32_e32 v154, s82, v172
	v_add_u32_e32 v156, 0x60, v154
	v_cmp_le_u32_e64 s[8:9], v156, v65
	v_cmp_ge_i32_e64 s[10:11], v156, v167
	v_add_u32_e32 v155, 64, v154
	s_and_b64 s[8:9], s[8:9], s[10:11]
	v_cmp_le_u32_e32 vcc, v155, v65
	v_cmp_ge_i32_e64 s[6:7], v155, v167
	v_cndmask_b32_e64 v82, v229, v82, s[8:9]
	v_add_u32_e32 v156, 0x41, v154
	v_cmp_lt_u32_e64 s[8:9], v155, v65
	v_add_u32_e32 v155, 0x61, v154
	v_cmp_le_u32_e64 s[12:13], v155, v65
	v_cmp_ge_i32_e64 s[10:11], v156, v167
	v_cmp_ge_i32_e64 s[14:15], v155, v167
	v_add_u32_e32 v156, 0x62, v154
	s_and_b64 s[12:13], s[12:13], s[14:15]
	v_add_u32_e32 v155, 0x42, v154
	v_cmp_le_u32_e64 s[16:17], v156, v65
	v_cmp_ge_i32_e64 s[18:19], v156, v167
	v_add_u32_e32 v156, 0x63, v154
	v_cndmask_b32_e64 v83, v229, v83, s[12:13]
	v_cmp_le_u32_e64 s[12:13], v155, v65
	v_cmp_ge_i32_e64 s[14:15], v155, v167
	s_and_b64 s[16:17], s[16:17], s[18:19]
	v_add_u32_e32 v155, 0x43, v154
	v_cmp_le_u32_e64 s[20:21], v156, v65
	v_cmp_ge_i32_e64 s[22:23], v156, v167
	v_add_u32_e32 v156, 0x68, v154
	v_cndmask_b32_e64 v84, v229, v84, s[16:17]
	v_cmp_le_u32_e64 s[16:17], v155, v65
	v_cmp_ge_i32_e64 s[18:19], v155, v167
	s_and_b64 s[20:21], s[20:21], s[22:23]
	v_add_u32_e32 v155, 0x48, v154
	v_cmp_le_u32_e64 s[24:25], v156, v65
	v_cmp_ge_i32_e64 s[26:27], v156, v167
	v_add_u32_e32 v156, 0x69, v154
	v_cndmask_b32_e64 v85, v229, v85, s[20:21]
	v_cmp_le_u32_e64 s[20:21], v155, v65
	v_cmp_ge_i32_e64 s[22:23], v155, v167
	s_and_b64 s[24:25], s[24:25], s[26:27]
	v_add_u32_e32 v155, 0x49, v154
	v_cmp_le_u32_e64 s[28:29], v156, v65
	v_cmp_ge_i32_e64 s[30:31], v156, v167
	v_add_u32_e32 v156, 0x6a, v154
	v_cndmask_b32_e64 v86, v229, v86, s[24:25]
	v_cmp_le_u32_e64 s[24:25], v155, v65
	v_cmp_ge_i32_e64 s[26:27], v155, v167
	s_and_b64 s[28:29], s[28:29], s[30:31]
	v_add_u32_e32 v155, 0x4a, v154
	v_cmp_le_u32_e64 s[34:35], v156, v65
	v_cmp_ge_i32_e64 s[36:37], v156, v167
	v_add_u32_e32 v156, 0x6b, v154
	v_cndmask_b32_e64 v87, v229, v87, s[28:29]
	v_cmp_le_u32_e64 s[28:29], v155, v65
	v_cmp_ge_i32_e64 s[30:31], v155, v167
	s_and_b64 s[34:35], s[34:35], s[36:37]
	v_add_u32_e32 v155, 0x4b, v154
	v_cmp_le_u32_e64 s[38:39], v156, v65
	v_cmp_ge_i32_e64 s[40:41], v156, v167
	v_add_u32_e32 v156, 0x70, v154
	v_cndmask_b32_e64 v88, v229, v88, s[34:35]
	v_cmp_le_u32_e64 s[34:35], v155, v65
	v_cmp_ge_i32_e64 s[36:37], v155, v167
	s_and_b64 s[38:39], s[38:39], s[40:41]
	v_add_u32_e32 v155, 0x50, v154
	v_cmp_le_u32_e64 s[42:43], v156, v65
	v_cmp_ge_i32_e64 s[44:45], v156, v167
	v_add_u32_e32 v156, 0x71, v154
	v_cndmask_b32_e64 v89, v229, v89, s[38:39]
	v_cmp_le_u32_e64 s[38:39], v155, v65
	v_cmp_ge_i32_e64 s[40:41], v155, v167
	s_and_b64 s[42:43], s[42:43], s[44:45]
	v_add_u32_e32 v155, 0x51, v154
	v_cmp_le_u32_e64 s[46:47], v156, v65
	v_cmp_ge_i32_e64 s[48:49], v156, v167
	v_add_u32_e32 v156, 0x72, v154
	v_cndmask_b32_e64 v90, v229, v90, s[42:43]
	v_cmp_le_u32_e64 s[42:43], v155, v65
	v_cmp_ge_i32_e64 s[44:45], v155, v167
	s_and_b64 s[46:47], s[46:47], s[48:49]
	v_add_u32_e32 v155, 0x52, v154
	v_cmp_le_u32_e64 s[50:51], v156, v65
	v_cmp_ge_i32_e64 s[52:53], v156, v167
	v_add_u32_e32 v156, 0x73, v154
	v_cndmask_b32_e64 v91, v229, v91, s[46:47]
	v_cmp_le_u32_e64 s[46:47], v155, v65
	v_cmp_ge_i32_e64 s[48:49], v155, v167
	s_and_b64 s[50:51], s[50:51], s[52:53]
	v_add_u32_e32 v155, 0x53, v154
	v_cmp_le_u32_e64 s[54:55], v156, v65
	v_cmp_ge_i32_e64 s[56:57], v156, v167
	v_add_u32_e32 v156, 0x78, v154
	v_cndmask_b32_e64 v92, v229, v92, s[50:51]
	v_cmp_le_u32_e64 s[50:51], v155, v65
	v_cmp_ge_i32_e64 s[52:53], v155, v167
	s_and_b64 s[54:55], s[54:55], s[56:57]
	v_add_u32_e32 v155, 0x58, v154
	v_cmp_le_u32_e64 s[58:59], v156, v65
	v_cmp_ge_i32_e64 s[60:61], v156, v167
	v_add_u32_e32 v156, 0x79, v154
	v_cndmask_b32_e64 v93, v229, v93, s[54:55]
	v_cmp_le_u32_e64 s[54:55], v155, v65
	v_cmp_ge_i32_e64 s[56:57], v155, v167
	s_and_b64 s[58:59], s[58:59], s[60:61]
	v_add_u32_e32 v155, 0x59, v154
	v_cmp_le_u32_e64 s[62:63], v156, v65
	v_cmp_ge_i32_e64 s[64:65], v156, v167
	v_cndmask_b32_e64 v94, v229, v94, s[58:59]
	v_cmp_le_u32_e64 s[58:59], v155, v65
	v_cmp_ge_i32_e64 s[60:61], v155, v167
	s_and_b64 s[62:63], s[62:63], s[64:65]
	v_add_u32_e32 v155, 0x5a, v154
	v_add_u32_e32 v156, 0x7a, v154
	v_cndmask_b32_e64 v95, v229, v95, s[62:63]
	v_cmp_le_u32_e64 s[62:63], v155, v65
	v_cmp_le_u32_e64 s[66:67], v156, v65
	v_cmp_ge_i32_e64 s[64:65], v155, v167
	v_cmp_ge_i32_e64 s[68:69], v156, v167
	v_add_u32_e32 v155, 0x5b, v154
	v_add_u32_e32 v154, 0x7b, v154
	s_and_b64 s[66:67], s[66:67], s[68:69]
	v_cmp_gt_u32_e64 s[70:71], v154, v65
	v_cmp_lt_i32_e64 s[72:73], v154, v167
	v_cndmask_b32_e64 v96, v229, v96, s[66:67]
	v_cmp_le_u32_e64 s[66:67], v155, v65
	v_cmp_ge_i32_e64 s[68:69], v155, v167
	s_or_b64 s[72:73], s[70:71], s[72:73]
	s_and_saveexec_b64 s[70:71], s[72:73]
	v_mov_b32_e32 v97, s0
	s_or_b64 exec, exec, s[70:71]
	s_and_b64 vcc, vcc, s[6:7]
	v_cndmask_b32_e32 v66, v229, v66, vcc
	s_and_b64 vcc, s[8:9], s[10:11]
	v_cndmask_b32_e32 v67, v229, v67, vcc
	s_and_b64 vcc, s[12:13], s[14:15]
	v_cndmask_b32_e32 v68, v229, v68, vcc
	s_and_b64 vcc, s[16:17], s[18:19]
	v_cndmask_b32_e32 v69, v229, v69, vcc
	s_and_b64 vcc, s[20:21], s[22:23]
	v_cndmask_b32_e32 v70, v229, v70, vcc
	s_and_b64 vcc, s[24:25], s[26:27]
	v_cndmask_b32_e32 v71, v229, v71, vcc
	s_and_b64 vcc, s[28:29], s[30:31]
	v_cndmask_b32_e32 v72, v229, v72, vcc
	s_and_b64 vcc, s[34:35], s[36:37]
	v_cndmask_b32_e32 v73, v229, v73, vcc
	s_and_b64 vcc, s[38:39], s[40:41]
	v_cndmask_b32_e32 v74, v229, v74, vcc
	s_and_b64 vcc, s[42:43], s[44:45]
	v_cndmask_b32_e32 v75, v229, v75, vcc
	s_and_b64 vcc, s[46:47], s[48:49]
	v_cndmask_b32_e32 v76, v229, v76, vcc
	s_and_b64 vcc, s[50:51], s[52:53]
	v_cndmask_b32_e32 v77, v229, v77, vcc
	s_and_b64 vcc, s[54:55], s[56:57]
	v_cndmask_b32_e32 v78, v229, v78, vcc
	s_and_b64 vcc, s[58:59], s[60:61]
	v_cndmask_b32_e32 v79, v229, v79, vcc
	s_and_b64 vcc, s[62:63], s[64:65]
	v_cndmask_b32_e32 v80, v229, v80, vcc
	s_and_b64 vcc, s[66:67], s[68:69]
	v_cndmask_b32_e32 v81, v229, v81, vcc
